# GEMM unit loop: next unit's tile coordinates from the closed form of the static order (no emulated integer divisions per unit)
# baseline (speedup 1.0000x reference)
.LBB0_481:
	s_add_i32 s27, s27, 1
	s_lshl_b32 s38, s27, 8
	s_add_i32 s38, s38, s12
	s_mov_b32 s39, 0
	v_mov_b64_e32 v[0:1], s[24:25]
	v_cmp_ge_i64_e32 vcc, s[38:39], v[0:1]
	v_cmp_lt_i64_e64 s[46:47], s[38:39], v[0:1]
	s_cbranch_vccnz .LBB0_483
	s_mov_b32 s93, s27
	s_and_b32 s94, s12, 7
	s_lshl_b32 s94, s94, 3
	s_bfe_u32 s44, s12, 0x30003
	s_add_i32 s94, s94, s44
	s_lshl_b32 s92, s27, 2
	s_lshr_b32 s44, s12, 6
	s_add_i32 s92, s92, s44
